# kstatic: K-loops without per-segment s_setprio flips, one static priority raise for waves 4-7 per GEMM phase; on top of v78
# speedup vs baseline: 1.0073x; 1.0073x over previous
; #define GAS __attribute__((address_space(1)))
; __device__ __forceinline__ int lane_id_opaque() { int l; asm volatile("v_mbcnt_lo_u32_b32 %0, -1, 0\n\tv_mbcnt_hi_u32_b32 %0, -1, %0" : "=&v"(l)); return l; }
; #define PG8_LAS __attribute__((address_space(3)))
; #define PG8_STAGE(bufoff, gbase, voff) do { _Pragma("unroll") for (int _i = 0; _i < 2; ++_i) \
;         __builtin_amdgcn_global_load_lds((const unsigned*)((const char*)(gbase) + (voff)[_i]), (PG8_LAS unsigned*)(lds + (bufoff) + ldsw + _i * 8192), 16, 0, 0); } while (0)
; #define PG8_WAIT_V(n) asm volatile("s_waitcnt vmcnt(" #n ")" ::: "memory")
; #define PG8_BAR __builtin_amdgcn_s_barrier()
; template <class Epi, class Sched, bool ALIGN_EPI = false, bool SP2 = true>
; __device__ __forceinline__ void gemm_phase(PG8_LAS unsigned char* lds, const Gemm g, const Sched& S, const Epi& E, int wave_s) {
;     ...
;         PG8_WAIT_V(2); PG8_BAR;
;         PG8_STAGE(PG8_SB(1, 0), cB + kstep, voffB); PG8_STAGE(PG8_SA(1, 0), cA + kstep, voffA); PG8_STAGE(PG8_SB(1, 1), cB + hstepB + kstep, voffB);
;         PG8_WAIT_V(6); PG8_BAR;
;     } else {
;         PG8_STAGE(PG8_SB(0, 0), cB, voffB); PG8_STAGE(PG8_SA(0, 0), cA, voffA); PG8_STAGE(PG8_SB(0, 1), cB + hstepB, voffB); PG8_STAGE(PG8_SA(0, 1), cA + hstepA, voffA);
;         if (wr == 1) PG8_BAR;
;         PG8_WAIT_V(4); PG8_BAR;
;         PG8_STAGE(PG8_SB(1, 0), cB + kstep, voffB); PG8_STAGE(PG8_SA(1, 0), cA + kstep, voffA); PG8_STAGE(PG8_SB(1, 1), cB + hstepB + kstep, voffB);
;         PG8_WAIT_V(6); PG8_BAR;
;     }
;     for (;;) {
;         const bool has_next = S.next(ui + 1, nxt);
;         const char* nA = has_next ? (const char*)g.A + (size_t)nxt.pm * tstepA : cA; const char* nB = has_next ? (const char*)g.Bt + (size_t)nxt.pn * tstepB : cB;
;         if (Epi::ROWTAB && wid < 4)
;             __builtin_amdgcn_global_load_lds((const GAS unsigned*)((const GAS char*)(E.rowtab + cur.pm * BM + wid * 64) + (size_t)(unsigned)(lane_id_opaque() * 4)), (PG8_LAS unsigned*)(lds + ROWTAB_OFF + (ui & 1) * 1024 + wid * 256), 4, 0, 0);
.LBB0_337:
	s_add_u32 s10, s86, 0x1ed00000
	s_addc_u32 s11, s87, 0
	s_add_u32 s14, s86, 0x1e900000
	s_addc_u32 s15, s87, 0
	s_and_b64 s[8:9], s[90:91], exec
	s_cselect_b32 s11, s11, s41
	s_cselect_b32 s10, s10, s40
	s_lshl_b32 s8, s1, 5
	s_and_b32 s43, s8, 0x60
	s_add_i32 m0, s35, 0x18000
	v_lshl_add_u64 v[8:9], v[8:9], 0, s[78:79]
	s_lshl_b32 s16, s3, 13
	s_lshl_b32 s17, s43, 7
	s_waitcnt vmcnt(2)
	s_barrier
	global_load_lds_dwordx4 v[8:9], off
	v_lshl_add_u64 v[6:7], v[6:7], 0, s[78:79]
	s_add_i32 m0, s35, 0x1a000
	s_add_i32 s44, s35, 0x8000
	s_add_i32 s45, s35, 0xa000
	global_load_lds_dwordx4 v[6:7], off
	v_lshl_add_u64 v[2:3], v[2:3], 0, s[78:79]
	s_mov_b32 m0, s44
	s_add_u32 s8, s4, 0x80080
	global_load_lds_dwordx4 v[2:3], off
	v_lshl_add_u64 v[2:3], v[4:5], 0, s[78:79]
	s_mov_b32 m0, s45
	s_addc_u32 s9, s5, 0
	global_load_lds_dwordx4 v[2:3], off
	s_add_i32 m0, s35, 0x1c000
	v_lshl_add_u64 v[2:3], s[8:9], 0, v[134:135]
	global_load_lds_dwordx4 v[2:3], off
	v_lshl_add_u64 v[2:3], s[8:9], 0, v[130:131]
	s_add_i32 m0, s35, 0x1e000
	s_cmp_lt_i32 s1, 4
	global_load_lds_dwordx4 v[2:3], off
	v_lshrrev_b32_e32 v3, 1, v11
	v_and_b32_e32 v138, 24, v3
	v_and_b32_e32 v2, 15, v11
	v_lshlrev_b32_e32 v3, 1, v138
	v_lshl_or_b32 v1, s3, 6, v2
	v_lshl_or_b32 v3, v2, 6, v3
	v_lshlrev_b32_e32 v2, 2, v2
	v_and_b32_e32 v4, 32, v2
	v_bitop3_b32 v5, v3, s16, v4 bitop3:0xde
	v_bitop3_b32 v139, v3, s17, v4 bitop3:0xde
	s_cselect_b64 s[16:17], -1, 0
	s_lshl_b32 s3, s3, 8
	s_add_i32 s3, s61, s3
	v_add_u32_e32 v172, s3, v2
	v_lshlrev_b32_e32 v2, 15, v10
	v_and_b32_e32 v2, 0xffff0000, v2
	v_lshl_add_u32 v2, v12, 12, v2
	v_and_b32_e32 v3, 1, v10
	s_and_b32 s8, s0, 0xffffffc0
	s_lshl_b32 s1, s1, 8
	v_lshl_or_b32 v2, v3, 6, v2
	s_ashr_i32 s9, s8, 31
	s_add_i32 s62, s61, s1
	v_lshl_add_u32 v140, v13, 1, v2
	v_lshlrev_b32_e32 v2, 15, v15
	s_cmpk_lt_u32 s0, 0x100
	v_and_b32_e32 v2, 0xffff0000, v2
	s_waitcnt vmcnt(6)
	s_cselect_b64 s[18:19], -1, 0
	s_lshl_b64 s[0:1], s[8:9], 2
	v_lshl_add_u32 v2, v14, 12, v2
	v_and_b32_e32 v3, 1, v15
	s_add_u32 s63, s10, s0
	v_lshl_or_b32 v2, v3, 6, v2
	v_readlane_b32 s8, v254, 33
	s_addc_u32 s92, s11, s1
	v_or_b32_e32 v173, s43, v138
	v_mov_b32_e32 v141, v0
	v_lshl_add_u32 v142, v16, 1, v2
	v_mov_b32_e32 v143, v0
	s_mov_b32 s3, 0
	v_add_u32_e32 v174, 0, v5
	s_cmp_lt_u32 s81, 0x100
	s_cbranch_scc1 .Lks_g1
	s_setprio 1
.Lks_g1:
	v_readlane_b32 s0, v254, 30
	s_mov_b32 s1, s8
	s_barrier
	v_readlane_b32 s9, v254, 34
	s_branch .LBB0_340

; #define PG8_STAGE(bufoff, gbase, voff) do { _Pragma("unroll") for (int _i = 0; _i < 2; ++_i) \
;         __builtin_amdgcn_global_load_lds((const unsigned*)((const char*)(gbase) + (voff)[_i]), (PG8_LAS unsigned*)(lds + (bufoff) + ldsw + _i * 8192), 16, 0, 0); } while (0)
; #define PG8_LDA(dst, b, h) do { _Pragma("unroll") for (int m = 0; m < 4; ++m) _Pragma("unroll") for (int k = 0; k < 2; ++k) dst[m][k] = *(const PG8_LAS bf16x8*)(lds + PG8_SA(b, h) + aoff + m * 2048 + k * 1024); } while (0)
; #define PG8_LDB(dst, b, h) do { _Pragma("unroll") for (int n = 0; n < 2; ++n) _Pragma("unroll") for (int k = 0; k < 2; ++k) dst[n][k] = *(const PG8_LAS bf16x8*)(lds + PG8_SB(b, h) + boff + n * 2048 + k * 1024); } while (0)
; #define PG8_MMA(ai, bj, At, Bt) do { __builtin_amdgcn_s_setprio(1); _Pragma("unroll") for (int m = 0; m < 4; ++m) _Pragma("unroll") for (int n = 0; n < 2; ++n) _Pragma("unroll") for (int k = 0; k < 2; ++k) \
;         acc[ai][bj][m][n] = __builtin_amdgcn_mfma_f32_16x16x32_bf16(Bt[n][k], At[m][k], acc[ai][bj][m][n], 0, 0, 0); __builtin_amdgcn_s_setprio(0); } while (0)
; #define PG8_WAIT_V(n) asm volatile("s_waitcnt vmcnt(" #n ")" ::: "memory")
; #define PG8_WAIT_L(n) asm volatile("s_waitcnt lgkmcnt(" #n ")" ::: "memory")
; #define PG8_BAR __builtin_amdgcn_s_barrier()
; #define PG8_SCHED __builtin_amdgcn_sched_barrier(0)
; template <class Epi, class Sched, bool ALIGN_EPI = false, bool SP2 = true>
; __device__ __forceinline__ void gemm_phase(PG8_LAS unsigned char* lds, const Gemm g, const Sched& S, const Epi& E, int wave_s) {
;     ...
;             PG8_LDB(B0, 0, 0); PG8_LDB(B1, 0, 1); PG8_SCHED; PG8_LDA(At, 0, 0); PG8_STAGE(PG8_SA(1, 1), a1 + hstepA, voffA);
;             PG8_WAIT_V(8); PG8_WAIT_L(0); PG8_BAR; PG8_MMA(0, 0, At, B0); PG8_MMA(0, 1, At, B1); PG8_BAR; PG8_SCHED;
;             PG8_LDA(At, 0, 1); PG8_STAGE(PG8_SB(0, 0), b2, voffB); PG8_STAGE(PG8_SB(0, 1), b2 + hstepB, voffB); PG8_STAGE(PG8_SA(0, 0), a2, voffA);
.LBB0_345:
	s_add_u32 s6, s4, 0xfff80080
	s_addc_u32 s7, s5, -1
	s_add_i32 s73, 0, 0x10000
	s_cmp_eq_u32 s72, 28
	s_cselect_b32 s11, s23, s7
	s_cselect_b32 s10, s28, s6
	v_add_u32_e32 v144, s73, v139
	s_cselect_b32 s7, s21, s46
	s_cselect_b32 s6, s29, s33
	s_add_i32 s76, 0, 0x14000
	ds_read_b128 v[154:157], v144
	ds_read_b128 v[158:161], v144 offset:1024
	ds_read_b128 v[162:165], v144 offset:2048
	ds_read_b128 v[166:169], v144 offset:3072
	v_add_u32_e32 v144, s76, v139
	ds_read_b128 v[176:179], v144
	ds_read_b128 v[180:183], v144 offset:1024
	ds_read_b128 v[184:187], v144 offset:2048
	ds_read_b128 v[188:191], v144 offset:3072
	v_lshl_add_u64 v[144:145], s[4:5], 0, v[142:143]
	s_add_i32 m0, s35, 0xc000
	ds_read_b128 v[192:195], v174
	ds_read_b128 v[196:199], v174 offset:1024
	ds_read_b128 v[200:203], v174 offset:2048
	ds_read_b128 v[204:207], v174 offset:3072
	ds_read_b128 v[208:211], v174 offset:4096
	ds_read_b128 v[212:215], v174 offset:5120
	ds_read_b128 v[216:219], v174 offset:6144
	ds_read_b128 v[220:223], v174 offset:7168
	global_load_lds_dwordx4 v[144:145], off
	v_lshl_add_u64 v[144:145], s[4:5], 0, v[140:141]
	s_add_i32 m0, s35, 0xe000
	s_nop 0
	global_load_lds_dwordx4 v[144:145], off
	s_waitcnt vmcnt(8)
	s_waitcnt lgkmcnt(0)
	s_barrier
	v_mfma_f32_16x16x32_bf16 v[126:129], v[154:157], v[192:195], v[126:129]
	v_mfma_f32_16x16x32_bf16 v[122:125], v[162:165], v[192:195], v[122:125]
	v_mfma_f32_16x16x32_bf16 v[110:113], v[154:157], v[200:203], v[110:113]
	v_mfma_f32_16x16x32_bf16 v[106:109], v[162:165], v[200:203], v[106:109]
	v_mfma_f32_16x16x32_bf16 v[94:97], v[154:157], v[208:211], v[94:97]
	v_mfma_f32_16x16x32_bf16 v[90:93], v[162:165], v[208:211], v[90:93]
	v_mfma_f32_16x16x32_bf16 v[78:81], v[154:157], v[216:219], v[78:81]
	v_mfma_f32_16x16x32_bf16 v[74:77], v[162:165], v[216:219], v[74:77]
	v_mfma_f32_16x16x32_bf16 v[126:129], v[158:161], v[196:199], v[126:129]
	v_mfma_f32_16x16x32_bf16 v[122:125], v[166:169], v[196:199], v[122:125]
	v_mfma_f32_16x16x32_bf16 v[110:113], v[158:161], v[204:207], v[110:113]
	v_mfma_f32_16x16x32_bf16 v[106:109], v[166:169], v[204:207], v[106:109]
	v_mfma_f32_16x16x32_bf16 v[94:97], v[158:161], v[212:215], v[94:97]
	v_mfma_f32_16x16x32_bf16 v[90:93], v[166:169], v[212:215], v[90:93]
	v_mfma_f32_16x16x32_bf16 v[78:81], v[158:161], v[220:223], v[78:81]
	v_mfma_f32_16x16x32_bf16 v[74:77], v[166:169], v[220:223], v[74:77]
	v_mfma_f32_16x16x32_bf16 v[118:121], v[176:179], v[192:195], v[118:121]
	v_mfma_f32_16x16x32_bf16 v[114:117], v[184:187], v[192:195], v[114:117]
	v_mfma_f32_16x16x32_bf16 v[102:105], v[176:179], v[200:203], v[102:105]
	v_mfma_f32_16x16x32_bf16 v[98:101], v[184:187], v[200:203], v[98:101]
	v_mfma_f32_16x16x32_bf16 v[86:89], v[176:179], v[208:211], v[86:89]
	v_mfma_f32_16x16x32_bf16 v[82:85], v[184:187], v[208:211], v[82:85]
	v_mfma_f32_16x16x32_bf16 v[70:73], v[176:179], v[216:219], v[70:73]
	v_mfma_f32_16x16x32_bf16 v[66:69], v[184:187], v[216:219], v[66:69]
	v_mfma_f32_16x16x32_bf16 v[118:121], v[180:183], v[196:199], v[118:121]
	v_mfma_f32_16x16x32_bf16 v[114:117], v[188:191], v[196:199], v[114:117]
	v_mfma_f32_16x16x32_bf16 v[102:105], v[180:183], v[204:207], v[102:105]
	v_mfma_f32_16x16x32_bf16 v[98:101], v[188:191], v[204:207], v[98:101]
	v_mfma_f32_16x16x32_bf16 v[86:89], v[180:183], v[212:215], v[86:89]
	v_mfma_f32_16x16x32_bf16 v[82:85], v[188:191], v[212:215], v[82:85]
	v_mfma_f32_16x16x32_bf16 v[70:73], v[180:183], v[220:223], v[70:73]
	v_mfma_f32_16x16x32_bf16 v[66:69], v[188:191], v[220:223], v[66:69]
	s_barrier
	s_add_i32 s73, s73, s34
	v_lshl_add_u64 v[144:145], s[6:7], 0, v[134:135]
	s_mov_b32 m0, s73
	ds_read_b128 v[192:195], v174 offset:16384
	ds_read_b128 v[196:199], v174 offset:17408
	ds_read_b128 v[200:203], v174 offset:18432
	ds_read_b128 v[204:207], v174 offset:19456
	ds_read_b128 v[208:211], v174 offset:20480
	ds_read_b128 v[212:215], v174 offset:21504
	ds_read_b128 v[216:219], v174 offset:22528
	ds_read_b128 v[220:223], v174 offset:23552
	global_load_lds_dwordx4 v[144:145], off
	s_add_i32 m0, s73, 0x2000
	s_add_u32 s74, s6, 0x80000
	v_lshl_add_u64 v[170:171], s[6:7], 0, v[130:131]
	s_addc_u32 s75, s7, 0
	s_add_i32 s73, s76, s34
	global_load_lds_dwordx4 v[170:171], off
	v_lshl_add_u64 v[224:225], s[74:75], 0, v[134:135]
	s_mov_b32 m0, s73
	v_lshl_add_u64 v[226:227], s[10:11], 0, v[132:133]
	global_load_lds_dwordx4 v[224:225], off
	v_lshl_add_u64 v[224:225], s[74:75], 0, v[130:131]
	s_add_i32 m0, s73, 0x2000
	s_nop 0
	global_load_lds_dwordx4 v[224:225], off
	v_lshl_add_u64 v[224:225], s[10:11], 0, v[136:137]
	s_mov_b32 m0, s35
	s_nop 0
	global_load_lds_dwordx4 v[224:225], off
	s_mov_b32 m0, s37
	s_nop 0
	global_load_lds_dwordx4 v[226:227], off
	s_waitcnt vmcnt(8)
	s_waitcnt lgkmcnt(0)
	s_barrier
; #define PG8_STAGE(bufoff, gbase, voff) do { _Pragma("unroll") for (int _i = 0; _i < 2; ++_i) \
;         __builtin_amdgcn_global_load_lds((const unsigned*)((const char*)(gbase) + (voff)[_i]), (PG8_LAS unsigned*)(lds + (bufoff) + ldsw + _i * 8192), 16, 0, 0); } while (0)
; #define PG8_LDA(dst, b, h) do { _Pragma("unroll") for (int m = 0; m < 4; ++m) _Pragma("unroll") for (int k = 0; k < 2; ++k) dst[m][k] = *(const PG8_LAS bf16x8*)(lds + PG8_SA(b, h) + aoff + m * 2048 + k * 1024); } while (0)
; #define PG8_LDB(dst, b, h) do { _Pragma("unroll") for (int n = 0; n < 2; ++n) _Pragma("unroll") for (int k = 0; k < 2; ++k) dst[n][k] = *(const PG8_LAS bf16x8*)(lds + PG8_SB(b, h) + boff + n * 2048 + k * 1024); } while (0)
; #define PG8_MMA(ai, bj, At, Bt) do { __builtin_amdgcn_s_setprio(1); _Pragma("unroll") for (int m = 0; m < 4; ++m) _Pragma("unroll") for (int n = 0; n < 2; ++n) _Pragma("unroll") for (int k = 0; k < 2; ++k) \
;         acc[ai][bj][m][n] = __builtin_amdgcn_mfma_f32_16x16x32_bf16(Bt[n][k], At[m][k], acc[ai][bj][m][n], 0, 0, 0); __builtin_amdgcn_s_setprio(0); } while (0)
; #define PG8_WAIT_V(n) asm volatile("s_waitcnt vmcnt(" #n ")" ::: "memory")
; #define PG8_WAIT_L(n) asm volatile("s_waitcnt lgkmcnt(" #n ")" ::: "memory")
; #define PG8_BAR __builtin_amdgcn_s_barrier()
; #define PG8_SCHED __builtin_amdgcn_sched_barrier(0)
; template <class Epi, class Sched, bool ALIGN_EPI = false, bool SP2 = true>
; __device__ __forceinline__ void gemm_phase(PG8_LAS unsigned char* lds, const Gemm g, const Sched& S, const Epi& E, int wave_s) {
;     ...
;             PG8_LDA(At, 0, 1); PG8_STAGE(PG8_SB(0, 0), b2, voffB); PG8_STAGE(PG8_SB(0, 1), b2 + hstepB, voffB); PG8_STAGE(PG8_SA(0, 0), a2, voffA);
;             PG8_WAIT_V(8); PG8_WAIT_L(0); PG8_BAR; PG8_MMA(1, 0, At, B0); PG8_MMA(1, 1, At, B1); PG8_BAR; PG8_SCHED;
;             PG8_LDB(B0, 1, 0); PG8_LDB(B1, 1, 1); PG8_SCHED; PG8_LDA(At, 1, 0); PG8_STAGE(PG8_SA(0, 1), a2 + hstepA, voffA);
;             PG8_WAIT_V(8); PG8_WAIT_L(0); PG8_BAR; PG8_MMA(0, 0, At, B0); PG8_MMA(0, 1, At, B1); PG8_BAR; PG8_SCHED;
	v_mfma_f32_16x16x32_bf16 v[62:65], v[154:157], v[192:195], v[62:65]
	v_mfma_f32_16x16x32_bf16 v[58:61], v[162:165], v[192:195], v[58:61]
	v_mfma_f32_16x16x32_bf16 v[46:49], v[154:157], v[200:203], v[46:49]
	v_mfma_f32_16x16x32_bf16 v[42:45], v[162:165], v[200:203], v[42:45]
	v_mfma_f32_16x16x32_bf16 v[30:33], v[154:157], v[208:211], v[30:33]
	v_mfma_f32_16x16x32_bf16 v[26:29], v[162:165], v[208:211], v[26:29]
	v_mfma_f32_16x16x32_bf16 v[14:17], v[154:157], v[216:219], v[14:17]
	v_mfma_f32_16x16x32_bf16 v[10:13], v[162:165], v[216:219], v[10:13]
	v_mfma_f32_16x16x32_bf16 v[62:65], v[158:161], v[196:199], v[62:65]
	v_mfma_f32_16x16x32_bf16 v[58:61], v[166:169], v[196:199], v[58:61]
	v_mfma_f32_16x16x32_bf16 v[46:49], v[158:161], v[204:207], v[46:49]
	v_mfma_f32_16x16x32_bf16 v[42:45], v[166:169], v[204:207], v[42:45]
	v_mfma_f32_16x16x32_bf16 v[30:33], v[158:161], v[212:215], v[30:33]
	v_mfma_f32_16x16x32_bf16 v[26:29], v[166:169], v[212:215], v[26:29]
	v_mfma_f32_16x16x32_bf16 v[14:17], v[158:161], v[220:223], v[14:17]
	v_mfma_f32_16x16x32_bf16 v[10:13], v[166:169], v[220:223], v[10:13]
	v_mfma_f32_16x16x32_bf16 v[54:57], v[176:179], v[192:195], v[54:57]
	v_mfma_f32_16x16x32_bf16 v[50:53], v[184:187], v[192:195], v[50:53]
	v_mfma_f32_16x16x32_bf16 v[38:41], v[176:179], v[200:203], v[38:41]
	v_mfma_f32_16x16x32_bf16 v[34:37], v[184:187], v[200:203], v[34:37]
	v_mfma_f32_16x16x32_bf16 v[22:25], v[176:179], v[208:211], v[22:25]
	v_mfma_f32_16x16x32_bf16 v[18:21], v[184:187], v[208:211], v[18:21]
	v_mfma_f32_16x16x32_bf16 v[6:9], v[176:179], v[216:219], v[6:9]
	v_mfma_f32_16x16x32_bf16 v[2:5], v[184:187], v[216:219], v[2:5]
	v_mfma_f32_16x16x32_bf16 v[54:57], v[180:183], v[196:199], v[54:57]
	v_mfma_f32_16x16x32_bf16 v[50:53], v[188:191], v[196:199], v[50:53]
	v_mfma_f32_16x16x32_bf16 v[38:41], v[180:183], v[204:207], v[38:41]
	v_mfma_f32_16x16x32_bf16 v[34:37], v[188:191], v[204:207], v[34:37]
	v_mfma_f32_16x16x32_bf16 v[22:25], v[180:183], v[212:215], v[22:25]
	v_mfma_f32_16x16x32_bf16 v[18:21], v[188:191], v[212:215], v[18:21]
	v_mfma_f32_16x16x32_bf16 v[6:9], v[180:183], v[220:223], v[6:9]
	v_mfma_f32_16x16x32_bf16 v[2:5], v[188:191], v[220:223], v[2:5]
	s_barrier
	s_add_i32 s73, 0, 0x18000
	v_add_u32_e32 v146, s73, v139
	s_add_i32 s74, 0, 0x1c000
	ds_read_b128 v[154:157], v146
	ds_read_b128 v[158:161], v146 offset:1024
	ds_read_b128 v[162:165], v146 offset:2048
	ds_read_b128 v[166:169], v146 offset:3072
	v_add_u32_e32 v146, s74, v139
	ds_read_b128 v[176:179], v146
	ds_read_b128 v[180:183], v146 offset:1024
	ds_read_b128 v[184:187], v146 offset:2048
	ds_read_b128 v[188:191], v146 offset:3072
	s_add_u32 s10, s10, 0x80000
	s_addc_u32 s11, s11, 0
	s_mov_b32 m0, s38
	v_lshl_add_u64 v[228:229], s[10:11], 0, v[136:137]
	ds_read_b128 v[192:195], v174 offset:32768
	ds_read_b128 v[196:199], v174 offset:33792
	ds_read_b128 v[200:203], v174 offset:34816
	ds_read_b128 v[204:207], v174 offset:35840
	ds_read_b128 v[208:211], v174 offset:36864
	ds_read_b128 v[212:215], v174 offset:37888
	ds_read_b128 v[216:219], v174 offset:38912
	ds_read_b128 v[220:223], v174 offset:39936
	global_load_lds_dwordx4 v[228:229], off
	v_lshl_add_u64 v[228:229], s[10:11], 0, v[132:133]
	s_mov_b32 m0, s39
	s_nop 0
	global_load_lds_dwordx4 v[228:229], off
	s_waitcnt vmcnt(8)
	s_waitcnt lgkmcnt(0)
	s_barrier
	v_mfma_f32_16x16x32_bf16 v[126:129], v[154:157], v[192:195], v[126:129]
	v_mfma_f32_16x16x32_bf16 v[122:125], v[162:165], v[192:195], v[122:125]
	v_mfma_f32_16x16x32_bf16 v[110:113], v[154:157], v[200:203], v[110:113]
	v_mfma_f32_16x16x32_bf16 v[106:109], v[162:165], v[200:203], v[106:109]
	v_mfma_f32_16x16x32_bf16 v[94:97], v[154:157], v[208:211], v[94:97]
	v_mfma_f32_16x16x32_bf16 v[90:93], v[162:165], v[208:211], v[90:93]
	v_mfma_f32_16x16x32_bf16 v[78:81], v[154:157], v[216:219], v[78:81]
	v_mfma_f32_16x16x32_bf16 v[74:77], v[162:165], v[216:219], v[74:77]
	v_mfma_f32_16x16x32_bf16 v[126:129], v[158:161], v[196:199], v[126:129]
	v_mfma_f32_16x16x32_bf16 v[122:125], v[166:169], v[196:199], v[122:125]
	v_mfma_f32_16x16x32_bf16 v[110:113], v[158:161], v[204:207], v[110:113]
	v_mfma_f32_16x16x32_bf16 v[106:109], v[166:169], v[204:207], v[106:109]
	v_mfma_f32_16x16x32_bf16 v[94:97], v[158:161], v[212:215], v[94:97]
	v_mfma_f32_16x16x32_bf16 v[90:93], v[166:169], v[212:215], v[90:93]
	v_mfma_f32_16x16x32_bf16 v[78:81], v[158:161], v[220:223], v[78:81]
	v_mfma_f32_16x16x32_bf16 v[74:77], v[166:169], v[220:223], v[74:77]
	v_mfma_f32_16x16x32_bf16 v[118:121], v[176:179], v[192:195], v[118:121]
	v_mfma_f32_16x16x32_bf16 v[114:117], v[184:187], v[192:195], v[114:117]
	v_mfma_f32_16x16x32_bf16 v[102:105], v[176:179], v[200:203], v[102:105]
	v_mfma_f32_16x16x32_bf16 v[98:101], v[184:187], v[200:203], v[98:101]
	v_mfma_f32_16x16x32_bf16 v[86:89], v[176:179], v[208:211], v[86:89]
	v_mfma_f32_16x16x32_bf16 v[82:85], v[184:187], v[208:211], v[82:85]
	v_mfma_f32_16x16x32_bf16 v[70:73], v[176:179], v[216:219], v[70:73]
	v_mfma_f32_16x16x32_bf16 v[66:69], v[184:187], v[216:219], v[66:69]
	v_mfma_f32_16x16x32_bf16 v[118:121], v[180:183], v[196:199], v[118:121]
	v_mfma_f32_16x16x32_bf16 v[114:117], v[188:191], v[196:199], v[114:117]
	v_mfma_f32_16x16x32_bf16 v[102:105], v[180:183], v[204:207], v[102:105]
	v_mfma_f32_16x16x32_bf16 v[98:101], v[188:191], v[204:207], v[98:101]
	v_mfma_f32_16x16x32_bf16 v[86:89], v[180:183], v[212:215], v[86:89]
	v_mfma_f32_16x16x32_bf16 v[82:85], v[188:191], v[212:215], v[82:85]
	v_mfma_f32_16x16x32_bf16 v[70:73], v[180:183], v[220:223], v[70:73]
	v_mfma_f32_16x16x32_bf16 v[66:69], v[188:191], v[220:223], v[66:69]
	s_barrier
; #define PG8_STAGE(bufoff, gbase, voff) do { _Pragma("unroll") for (int _i = 0; _i < 2; ++_i) \
;         __builtin_amdgcn_global_load_lds((const unsigned*)((const char*)(gbase) + (voff)[_i]), (PG8_LAS unsigned*)(lds + (bufoff) + ldsw + _i * 8192), 16, 0, 0); } while (0)
; #define PG8_LDA(dst, b, h) do { _Pragma("unroll") for (int m = 0; m < 4; ++m) _Pragma("unroll") for (int k = 0; k < 2; ++k) dst[m][k] = *(const PG8_LAS bf16x8*)(lds + PG8_SA(b, h) + aoff + m * 2048 + k * 1024); } while (0)
; #define PG8_MMA(ai, bj, At, Bt) do { __builtin_amdgcn_s_setprio(1); _Pragma("unroll") for (int m = 0; m < 4; ++m) _Pragma("unroll") for (int n = 0; n < 2; ++n) _Pragma("unroll") for (int k = 0; k < 2; ++k) \
;         acc[ai][bj][m][n] = __builtin_amdgcn_mfma_f32_16x16x32_bf16(Bt[n][k], At[m][k], acc[ai][bj][m][n], 0, 0, 0); __builtin_amdgcn_s_setprio(0); } while (0)
; #define PG8_WAIT_V(n) asm volatile("s_waitcnt vmcnt(" #n ")" ::: "memory")
; #define PG8_WAIT_L(n) asm volatile("s_waitcnt lgkmcnt(" #n ")" ::: "memory")
; #define PG8_BAR __builtin_amdgcn_s_barrier()
; #define PG8_SCHED __builtin_amdgcn_sched_barrier(0)
; template <class Epi, class Sched, bool ALIGN_EPI = false, bool SP2 = true>
; __device__ __forceinline__ void gemm_phase(PG8_LAS unsigned char* lds, const Gemm g, const Sched& S, const Epi& E, int wave_s) {
;     ...
;         for (int t = 0; t < nt; t += 2) {
;             const bool last = (t == nt - 2);
;     ...
;             PG8_LDA(At, 1, 1); PG8_STAGE(PG8_SB(1, 0), b3, voffB); PG8_STAGE(PG8_SB(1, 1), b3 + hstepB, voffB); PG8_STAGE(PG8_SA(1, 0), a3, voffA);
;             PG8_WAIT_V(8); PG8_WAIT_L(0); PG8_BAR; PG8_MMA(1, 0, At, B0); PG8_MMA(1, 1, At, B1); PG8_BAR; PG8_SCHED;
	s_add_i32 s10, s73, s34
	v_lshl_add_u64 v[144:145], v[144:145], 0, s[78:79]
	s_mov_b32 m0, s10
	ds_read_b128 v[192:195], v174 offset:49152
	ds_read_b128 v[196:199], v174 offset:50176
	ds_read_b128 v[200:203], v174 offset:51200
	ds_read_b128 v[204:207], v174 offset:52224
	ds_read_b128 v[208:211], v174 offset:53248
	ds_read_b128 v[212:215], v174 offset:54272
	ds_read_b128 v[216:219], v174 offset:55296
	ds_read_b128 v[220:223], v174 offset:56320
	global_load_lds_dwordx4 v[144:145], off
	s_add_i32 m0, s10, 0x2000
	s_add_u32 s6, s6, 0x80080
	v_lshl_add_u64 v[144:145], v[170:171], 0, s[78:79]
	s_addc_u32 s7, s7, 0
	s_add_i32 s10, s74, s34
	global_load_lds_dwordx4 v[144:145], off
	v_lshl_add_u64 v[144:145], s[6:7], 0, v[134:135]
	s_mov_b32 m0, s10
	s_nop 0
	global_load_lds_dwordx4 v[144:145], off
	v_lshl_add_u64 v[144:145], s[6:7], 0, v[130:131]
	s_add_i32 m0, s10, 0x2000
	s_nop 0
	global_load_lds_dwordx4 v[144:145], off
	v_lshl_add_u64 v[144:145], v[224:225], 0, s[78:79]
	s_mov_b32 m0, s44
	s_nop 0
	global_load_lds_dwordx4 v[144:145], off
	v_lshl_add_u64 v[144:145], v[226:227], 0, s[78:79]
	s_mov_b32 m0, s45
	s_nop 0
	global_load_lds_dwordx4 v[144:145], off
	s_waitcnt vmcnt(8)
	s_waitcnt lgkmcnt(0)
	s_barrier
	v_mfma_f32_16x16x32_bf16 v[62:65], v[154:157], v[192:195], v[62:65]
	v_mfma_f32_16x16x32_bf16 v[58:61], v[162:165], v[192:195], v[58:61]
	v_mfma_f32_16x16x32_bf16 v[46:49], v[154:157], v[200:203], v[46:49]
	v_mfma_f32_16x16x32_bf16 v[42:45], v[162:165], v[200:203], v[42:45]
	v_mfma_f32_16x16x32_bf16 v[30:33], v[154:157], v[208:211], v[30:33]
	v_mfma_f32_16x16x32_bf16 v[26:29], v[162:165], v[208:211], v[26:29]
	v_mfma_f32_16x16x32_bf16 v[14:17], v[154:157], v[216:219], v[14:17]
	v_mfma_f32_16x16x32_bf16 v[10:13], v[162:165], v[216:219], v[10:13]
	v_mfma_f32_16x16x32_bf16 v[62:65], v[158:161], v[196:199], v[62:65]
	v_mfma_f32_16x16x32_bf16 v[58:61], v[166:169], v[196:199], v[58:61]
	v_mfma_f32_16x16x32_bf16 v[46:49], v[158:161], v[204:207], v[46:49]
	v_mfma_f32_16x16x32_bf16 v[42:45], v[166:169], v[204:207], v[42:45]
	v_mfma_f32_16x16x32_bf16 v[30:33], v[158:161], v[212:215], v[30:33]
	v_mfma_f32_16x16x32_bf16 v[26:29], v[166:169], v[212:215], v[26:29]
	v_mfma_f32_16x16x32_bf16 v[14:17], v[158:161], v[220:223], v[14:17]
	v_mfma_f32_16x16x32_bf16 v[10:13], v[166:169], v[220:223], v[10:13]
	v_mfma_f32_16x16x32_bf16 v[54:57], v[176:179], v[192:195], v[54:57]
	v_mfma_f32_16x16x32_bf16 v[50:53], v[184:187], v[192:195], v[50:53]
	v_mfma_f32_16x16x32_bf16 v[38:41], v[176:179], v[200:203], v[38:41]
	v_mfma_f32_16x16x32_bf16 v[34:37], v[184:187], v[200:203], v[34:37]
	v_mfma_f32_16x16x32_bf16 v[22:25], v[176:179], v[208:211], v[22:25]
	v_mfma_f32_16x16x32_bf16 v[18:21], v[184:187], v[208:211], v[18:21]
	v_mfma_f32_16x16x32_bf16 v[6:9], v[176:179], v[216:219], v[6:9]
	v_mfma_f32_16x16x32_bf16 v[2:5], v[184:187], v[216:219], v[2:5]
	v_mfma_f32_16x16x32_bf16 v[54:57], v[180:183], v[196:199], v[54:57]
	v_mfma_f32_16x16x32_bf16 v[50:53], v[188:191], v[196:199], v[50:53]
	v_mfma_f32_16x16x32_bf16 v[38:41], v[180:183], v[204:207], v[38:41]
	v_mfma_f32_16x16x32_bf16 v[34:37], v[188:191], v[204:207], v[34:37]
	v_mfma_f32_16x16x32_bf16 v[22:25], v[180:183], v[212:215], v[22:25]
	v_mfma_f32_16x16x32_bf16 v[18:21], v[188:191], v[212:215], v[18:21]
	v_mfma_f32_16x16x32_bf16 v[6:9], v[180:183], v[220:223], v[6:9]
	v_mfma_f32_16x16x32_bf16 v[2:5], v[188:191], v[220:223], v[2:5]
	s_barrier
	s_add_i32 s72, s72, 2
	s_add_u32 s33, s33, 0x100
	s_addc_u32 s46, s46, 0
	s_add_u32 s4, s4, 0x100
	s_addc_u32 s5, s5, 0
	s_cmp_gt_u32 s72, 29
	s_cbranch_scc0 .LBB0_345
	s_and_b64 vcc, exec, s[18:19]
	s_cbranch_vccz .LBB0_348
	s_barrier

; #define PG8_WAIT_V(n) asm volatile("s_waitcnt vmcnt(" #n ")" ::: "memory")
; #define PG8_BAR __builtin_amdgcn_s_barrier()
; template <class Epi, class Sched, bool ALIGN_EPI = false, bool SP2 = true>
; __device__ __forceinline__ void gemm_phase(PG8_LAS unsigned char* lds, const Gemm g, const Sched& S, const Epi& E, int wave_s) {
;     ...
;     PG8_WAIT_V(0);
;     if constexpr (!ALIGN_EPI) { if (wr == 0) PG8_BAR; }
;     PG8_BAR;
.LBB0_415:
	s_setprio 0
	s_waitcnt vmcnt(0)
	s_barrier

; #define GAS __attribute__((address_space(1)))
; __device__ __forceinline__ int lane_id_opaque() { int l; asm volatile("v_mbcnt_lo_u32_b32 %0, -1, 0\n\tv_mbcnt_hi_u32_b32 %0, -1, %0" : "=&v"(l)); return l; }
; #define PG8_LAS __attribute__((address_space(3)))
; #define PG8_STAGE(bufoff, gbase, voff) do { _Pragma("unroll") for (int _i = 0; _i < 2; ++_i) \
;         __builtin_amdgcn_global_load_lds((const unsigned*)((const char*)(gbase) + (voff)[_i]), (PG8_LAS unsigned*)(lds + (bufoff) + ldsw + _i * 8192), 16, 0, 0); } while (0)
; #define PG8_WAIT_V(n) asm volatile("s_waitcnt vmcnt(" #n ")" ::: "memory")
; #define PG8_BAR __builtin_amdgcn_s_barrier()
; template <class Epi, class Sched, bool ALIGN_EPI = false, bool SP2 = true>
; __device__ __forceinline__ void gemm_phase(PG8_LAS unsigned char* lds, const Gemm g, const Sched& S, const Epi& E, int wave_s) {
;     ...
;         PG8_WAIT_V(2); PG8_BAR;
;         PG8_STAGE(PG8_SB(1, 0), cB + kstep, voffB); PG8_STAGE(PG8_SA(1, 0), cA + kstep, voffA); PG8_STAGE(PG8_SB(1, 1), cB + hstepB + kstep, voffB);
;         PG8_WAIT_V(6); PG8_BAR;
;     } else {
;         PG8_STAGE(PG8_SB(0, 0), cB, voffB); PG8_STAGE(PG8_SA(0, 0), cA, voffA); PG8_STAGE(PG8_SB(0, 1), cB + hstepB, voffB); PG8_STAGE(PG8_SA(0, 1), cA + hstepA, voffA);
;         if (wr == 1) PG8_BAR;
;         PG8_WAIT_V(4); PG8_BAR;
;         PG8_STAGE(PG8_SB(1, 0), cB + kstep, voffB); PG8_STAGE(PG8_SA(1, 0), cA + kstep, voffA); PG8_STAGE(PG8_SB(1, 1), cB + hstepB + kstep, voffB);
;         PG8_WAIT_V(6); PG8_BAR;
;     }
;     for (;;) {
;         const bool has_next = S.next(ui + 1, nxt);
;         const char* nA = has_next ? (const char*)g.A + (size_t)nxt.pm * tstepA : cA; const char* nB = has_next ? (const char*)g.Bt + (size_t)nxt.pn * tstepB : cB;
;         if (Epi::ROWTAB && wid < 4)
;             __builtin_amdgcn_global_load_lds((const GAS unsigned*)((const GAS char*)(E.rowtab + cur.pm * BM + wid * 64) + (size_t)(unsigned)(lane_id_opaque() * 4)), (PG8_LAS unsigned*)(lds + ROWTAB_OFF + (ui & 1) * 1024 + wid * 256), 4, 0, 0);
.LBB0_594:
	v_bfe_u32 v19, v1, 4, 2
	v_and_b32_e32 v18, 15, v1
	v_lshlrev_b32_e32 v20, 4, v19
	s_and_b64 s[4:5], s[90:91], exec
	v_lshl_or_b32 v1, s3, 6, v18
	v_lshl_or_b32 v20, v18, 6, v20
	v_lshlrev_b32_e32 v18, 2, v18
	s_cselect_b32 s13, s41, s39
	s_cselect_b32 s12, s40, s38
	s_lshl_b32 s4, s3, 13
	v_and_b32_e32 v21, 32, v18
	v_bitop3_b32 v22, v20, s4, v21 bitop3:0xde
	s_lshl_b32 s4, s1, 5
	s_and_b32 s6, s4, 0x60
	s_add_i32 m0, s35, 0x18000
	v_lshl_add_u64 v[8:9], v[8:9], 0, s[78:79]
	s_lshl_b32 s4, s6, 7
	s_waitcnt vmcnt(2)
	s_barrier
	global_load_lds_dwordx4 v[8:9], off
	v_lshl_add_u64 v[6:7], v[6:7], 0, s[78:79]
	s_add_i32 m0, s35, 0x1a000
	s_add_i32 s40, s35, 0x8000
	s_add_i32 s41, s35, 0xa000
	v_bitop3_b32 v170, v20, s4, v21 bitop3:0xde
	global_load_lds_dwordx4 v[6:7], off
	v_lshl_add_u64 v[2:3], v[2:3], 0, s[78:79]
	s_mov_b32 m0, s40
	s_add_u32 s4, s26, 0x80080
	global_load_lds_dwordx4 v[2:3], off
	v_lshl_add_u64 v[2:3], v[4:5], 0, s[78:79]
	s_mov_b32 m0, s41
	s_addc_u32 s5, s27, 0
	global_load_lds_dwordx4 v[2:3], off
	s_add_i32 m0, s35, 0x1c000
	v_lshl_add_u64 v[2:3], s[4:5], 0, v[142:143]
	global_load_lds_dwordx4 v[2:3], off
	v_lshl_add_u64 v[2:3], s[4:5], 0, v[138:139]
	s_add_i32 m0, s35, 0x1e000
	s_cmp_lt_i32 s1, 4
	global_load_lds_dwordx4 v[2:3], off
	s_cselect_b64 s[14:15], -1, 0
	s_lshl_b32 s3, s3, 8
	s_and_b32 s4, s0, 0xffffffc0
	s_lshl_b32 s1, s1, 8
	s_add_i32 s3, s61, s3
	s_ashr_i32 s5, s4, 31
	s_add_i32 s44, s61, s1
	s_cmpk_lt_u32 s0, 0x100
	s_cselect_b64 s[16:17], -1, 0
	s_lshl_b64 s[4:5], s[4:5], 2
	s_add_u32 s0, s86, s4
	v_add_u32_e32 v171, s3, v18
	v_lshlrev_b32_e32 v2, 6, v19
	s_addc_u32 s3, s87, s5
	v_bitop3_b32 v172, v2, 64, v18 bitop3:0x36
	s_add_u32 s45, s0, 0x1ed60000
	v_lshrrev_b32_e32 v3, 1, v10
	v_mul_lo_u32 v2, v11, s51
	s_mov_b32 s0, 0x14000
	v_mad_u64_u32 v[2:3], s[4:5], v3, s0, v[2:3]
	v_or_b32_e32 v2, v2, v12
	v_lshl_or_b32 v173, v19, 3, s6
	v_add_lshl_u32 v2, v2, v13, 1
	v_mov_b32_e32 v3, v0
	s_mov_b64 s[6:7], 0x140080
	v_lshl_add_u64 v[154:155], v[2:3], 0, s[6:7]
	v_lshrrev_b32_e32 v3, 1, v15
	v_mul_lo_u32 v2, v14, s51
	v_mad_u64_u32 v[2:3], s[4:5], v3, s0, v[2:3]
	s_waitcnt vmcnt(6)
	v_or_b32_e32 v2, v2, v16
	v_add_lshl_u32 v2, v2, v17, 1
	v_mov_b32_e32 v3, v0
	s_mov_b32 s1, 0
	v_cmp_eq_u32_e64 s[8:9], 0, v19
	s_addc_u32 s46, s3, 0
	v_lshl_add_u64 v[156:157], v[2:3], 0, s[6:7]
	v_add_u32_e32 v174, 0, v22
	s_cmp_lt_u32 s81, 0x100
	s_cbranch_scc1 .Lks_g3
	s_setprio 1
.Lks_g3:
	v_readlane_b32 s0, v254, 32
	v_readlane_b32 s3, v254, 31
	s_barrier
	s_branch .LBB0_597

; #define PG8_STAGE(bufoff, gbase, voff) do { _Pragma("unroll") for (int _i = 0; _i < 2; ++_i) \
;         __builtin_amdgcn_global_load_lds((const unsigned*)((const char*)(gbase) + (voff)[_i]), (PG8_LAS unsigned*)(lds + (bufoff) + ldsw + _i * 8192), 16, 0, 0); } while (0)
; #define PG8_LDA(dst, b, h) do { _Pragma("unroll") for (int m = 0; m < 4; ++m) _Pragma("unroll") for (int k = 0; k < 2; ++k) dst[m][k] = *(const PG8_LAS bf16x8*)(lds + PG8_SA(b, h) + aoff + m * 2048 + k * 1024); } while (0)
; #define PG8_LDB(dst, b, h) do { _Pragma("unroll") for (int n = 0; n < 2; ++n) _Pragma("unroll") for (int k = 0; k < 2; ++k) dst[n][k] = *(const PG8_LAS bf16x8*)(lds + PG8_SB(b, h) + boff + n * 2048 + k * 1024); } while (0)
; #define PG8_MMA(ai, bj, At, Bt) do { __builtin_amdgcn_s_setprio(1); _Pragma("unroll") for (int m = 0; m < 4; ++m) _Pragma("unroll") for (int n = 0; n < 2; ++n) _Pragma("unroll") for (int k = 0; k < 2; ++k) \
;         acc[ai][bj][m][n] = __builtin_amdgcn_mfma_f32_16x16x32_bf16(Bt[n][k], At[m][k], acc[ai][bj][m][n], 0, 0, 0); __builtin_amdgcn_s_setprio(0); } while (0)
; #define PG8_WAIT_V(n) asm volatile("s_waitcnt vmcnt(" #n ")" ::: "memory")
; #define PG8_WAIT_L(n) asm volatile("s_waitcnt lgkmcnt(" #n ")" ::: "memory")
; #define PG8_BAR __builtin_amdgcn_s_barrier()
; #define PG8_SCHED __builtin_amdgcn_sched_barrier(0)
; template <class Epi, class Sched, bool ALIGN_EPI = false, bool SP2 = true>
; __device__ __forceinline__ void gemm_phase(PG8_LAS unsigned char* lds, const Gemm g, const Sched& S, const Epi& E, int wave_s) {
;     ...
;             PG8_LDB(B0, 0, 0); PG8_LDB(B1, 0, 1); PG8_SCHED; PG8_LDA(At, 0, 0); PG8_STAGE(PG8_SA(1, 1), a1 + hstepA, voffA);
;             PG8_WAIT_V(8); PG8_WAIT_L(0); PG8_BAR; PG8_MMA(0, 0, At, B0); PG8_MMA(0, 1, At, B1); PG8_BAR; PG8_SCHED;
;             PG8_LDA(At, 0, 1); PG8_STAGE(PG8_SB(0, 0), b2, voffB); PG8_STAGE(PG8_SB(0, 1), b2 + hstepB, voffB); PG8_STAGE(PG8_SA(0, 0), a2, voffA);
.LBB0_608:
	s_add_u32 s6, s24, 0x100
	s_addc_u32 s7, s25, 0
	s_add_i32 s75, 0, 0x10000
	s_cmp_eq_u32 s74, 28
	s_cselect_b32 s29, s21, s7
	s_cselect_b32 s28, s20, s6
	v_add_u32_e32 v146, s75, v170
	s_cselect_b32 s27, s19, s73
	s_cselect_b32 s26, s33, s72
	s_add_i32 s76, 0, 0x14000
	ds_read_b128 v[130:133], v146
	ds_read_b128 v[134:137], v146 offset:1024
	ds_read_b128 v[158:161], v146 offset:2048
	ds_read_b128 v[162:165], v146 offset:3072
	v_add_u32_e32 v146, s76, v170
	ds_read_b128 v[166:169], v146
	ds_read_b128 v[176:179], v146 offset:1024
	ds_read_b128 v[180:183], v146 offset:2048
	ds_read_b128 v[184:187], v146 offset:3072
	v_lshl_add_u64 v[146:147], s[24:25], 0, v[156:157]
	s_add_i32 m0, s35, 0xc000
	ds_read_b128 v[188:191], v174
	ds_read_b128 v[192:195], v174 offset:1024
	ds_read_b128 v[196:199], v174 offset:2048
	ds_read_b128 v[200:203], v174 offset:3072
	ds_read_b128 v[204:207], v174 offset:4096
	ds_read_b128 v[208:211], v174 offset:5120
	ds_read_b128 v[212:215], v174 offset:6144
	ds_read_b128 v[216:219], v174 offset:7168
	global_load_lds_dwordx4 v[146:147], off
	v_lshl_add_u64 v[146:147], s[24:25], 0, v[154:155]
	s_add_i32 m0, s35, 0xe000
	s_nop 0
	global_load_lds_dwordx4 v[146:147], off
	s_waitcnt vmcnt(8)
	s_waitcnt lgkmcnt(0)
	s_barrier
	v_mfma_f32_16x16x32_bf16 v[126:129], v[130:133], v[188:191], v[126:129]
	v_mfma_f32_16x16x32_bf16 v[122:125], v[158:161], v[188:191], v[122:125]
	v_mfma_f32_16x16x32_bf16 v[110:113], v[130:133], v[196:199], v[110:113]
	v_mfma_f32_16x16x32_bf16 v[106:109], v[158:161], v[196:199], v[106:109]
	v_mfma_f32_16x16x32_bf16 v[94:97], v[130:133], v[204:207], v[94:97]
	v_mfma_f32_16x16x32_bf16 v[90:93], v[158:161], v[204:207], v[90:93]
	v_mfma_f32_16x16x32_bf16 v[78:81], v[130:133], v[212:215], v[78:81]
	v_mfma_f32_16x16x32_bf16 v[74:77], v[158:161], v[212:215], v[74:77]
	v_mfma_f32_16x16x32_bf16 v[126:129], v[134:137], v[192:195], v[126:129]
	v_mfma_f32_16x16x32_bf16 v[122:125], v[162:165], v[192:195], v[122:125]
	v_mfma_f32_16x16x32_bf16 v[110:113], v[134:137], v[200:203], v[110:113]
	v_mfma_f32_16x16x32_bf16 v[106:109], v[162:165], v[200:203], v[106:109]
	v_mfma_f32_16x16x32_bf16 v[94:97], v[134:137], v[208:211], v[94:97]
	v_mfma_f32_16x16x32_bf16 v[90:93], v[162:165], v[208:211], v[90:93]
	v_mfma_f32_16x16x32_bf16 v[78:81], v[134:137], v[216:219], v[78:81]
	v_mfma_f32_16x16x32_bf16 v[74:77], v[162:165], v[216:219], v[74:77]
	v_mfma_f32_16x16x32_bf16 v[118:121], v[166:169], v[188:191], v[118:121]
	v_mfma_f32_16x16x32_bf16 v[114:117], v[180:183], v[188:191], v[114:117]
	v_mfma_f32_16x16x32_bf16 v[102:105], v[166:169], v[196:199], v[102:105]
	v_mfma_f32_16x16x32_bf16 v[98:101], v[180:183], v[196:199], v[98:101]
	v_mfma_f32_16x16x32_bf16 v[86:89], v[166:169], v[204:207], v[86:89]
	v_mfma_f32_16x16x32_bf16 v[82:85], v[180:183], v[204:207], v[82:85]
	v_mfma_f32_16x16x32_bf16 v[70:73], v[166:169], v[212:215], v[70:73]
	v_mfma_f32_16x16x32_bf16 v[66:69], v[180:183], v[212:215], v[66:69]
	v_mfma_f32_16x16x32_bf16 v[118:121], v[176:179], v[192:195], v[118:121]
	v_mfma_f32_16x16x32_bf16 v[114:117], v[184:187], v[192:195], v[114:117]
	v_mfma_f32_16x16x32_bf16 v[102:105], v[176:179], v[200:203], v[102:105]
	v_mfma_f32_16x16x32_bf16 v[98:101], v[184:187], v[200:203], v[98:101]
	v_mfma_f32_16x16x32_bf16 v[86:89], v[176:179], v[208:211], v[86:89]
	v_mfma_f32_16x16x32_bf16 v[82:85], v[184:187], v[208:211], v[82:85]
	v_mfma_f32_16x16x32_bf16 v[70:73], v[176:179], v[216:219], v[70:73]
	v_mfma_f32_16x16x32_bf16 v[66:69], v[184:187], v[216:219], v[66:69]
	s_barrier
	s_add_i32 s24, s75, s34
	v_lshl_add_u64 v[146:147], s[26:27], 0, v[142:143]
	s_mov_b32 m0, s24
	ds_read_b128 v[188:191], v174 offset:16384
	ds_read_b128 v[192:195], v174 offset:17408
	ds_read_b128 v[196:199], v174 offset:18432
	ds_read_b128 v[200:203], v174 offset:19456
	ds_read_b128 v[204:207], v174 offset:20480
	ds_read_b128 v[208:211], v174 offset:21504
	ds_read_b128 v[212:215], v174 offset:22528
	ds_read_b128 v[216:219], v174 offset:23552
	global_load_lds_dwordx4 v[146:147], off
	s_add_i32 m0, s24, 0x2000
	s_add_u32 s24, s26, 0x80000
	v_lshl_add_u64 v[220:221], s[26:27], 0, v[138:139]
	s_addc_u32 s25, s27, 0
	s_add_i32 s75, s76, s34
	global_load_lds_dwordx4 v[220:221], off
	v_lshl_add_u64 v[222:223], s[24:25], 0, v[142:143]
	s_mov_b32 m0, s75
	v_lshl_add_u64 v[224:225], s[28:29], 0, v[140:141]
	global_load_lds_dwordx4 v[222:223], off
	v_lshl_add_u64 v[222:223], s[24:25], 0, v[138:139]
	s_add_i32 m0, s75, 0x2000
	s_nop 0
	global_load_lds_dwordx4 v[222:223], off
	v_lshl_add_u64 v[222:223], s[28:29], 0, v[144:145]
	s_mov_b32 m0, s35
	s_nop 0
	global_load_lds_dwordx4 v[222:223], off
	s_mov_b32 m0, s37
	s_nop 0
	global_load_lds_dwordx4 v[224:225], off
	s_cmp_lt_i32 s74, 0
	s_cbranch_scc1 .Lrf_join
	s_cmp_eq_u32 s92, 0
	s_cbranch_scc1 .Lrf_tree
	v_lshlrev_b32_e32 v240, 16, v228
	v_and_b32_e32 v241, 0xffff0000, v228
	v_lshlrev_b32_e32 v242, 16, v229
	v_and_b32_e32 v243, 0xffff0000, v229
	v_lshlrev_b32_e32 v244, 16, v230
	v_and_b32_e32 v245, 0xffff0000, v230
	v_lshlrev_b32_e32 v246, 16, v231
	v_and_b32_e32 v247, 0xffff0000, v231

; #define PG8_STAGE(bufoff, gbase, voff) do { _Pragma("unroll") for (int _i = 0; _i < 2; ++_i) \
;         __builtin_amdgcn_global_load_lds((const unsigned*)((const char*)(gbase) + (voff)[_i]), (PG8_LAS unsigned*)(lds + (bufoff) + ldsw + _i * 8192), 16, 0, 0); } while (0)
; #define PG8_LDA(dst, b, h) do { _Pragma("unroll") for (int m = 0; m < 4; ++m) _Pragma("unroll") for (int k = 0; k < 2; ++k) dst[m][k] = *(const PG8_LAS bf16x8*)(lds + PG8_SA(b, h) + aoff + m * 2048 + k * 1024); } while (0)
; #define PG8_LDB(dst, b, h) do { _Pragma("unroll") for (int n = 0; n < 2; ++n) _Pragma("unroll") for (int k = 0; k < 2; ++k) dst[n][k] = *(const PG8_LAS bf16x8*)(lds + PG8_SB(b, h) + boff + n * 2048 + k * 1024); } while (0)
; #define PG8_MMA(ai, bj, At, Bt) do { __builtin_amdgcn_s_setprio(1); _Pragma("unroll") for (int m = 0; m < 4; ++m) _Pragma("unroll") for (int n = 0; n < 2; ++n) _Pragma("unroll") for (int k = 0; k < 2; ++k) \
;         acc[ai][bj][m][n] = __builtin_amdgcn_mfma_f32_16x16x32_bf16(Bt[n][k], At[m][k], acc[ai][bj][m][n], 0, 0, 0); __builtin_amdgcn_s_setprio(0); } while (0)
; #define PG8_WAIT_V(n) asm volatile("s_waitcnt vmcnt(" #n ")" ::: "memory")
; #define PG8_WAIT_L(n) asm volatile("s_waitcnt lgkmcnt(" #n ")" ::: "memory")
; #define PG8_BAR __builtin_amdgcn_s_barrier()
; #define PG8_SCHED __builtin_amdgcn_sched_barrier(0)
; template <class Epi, class Sched, bool ALIGN_EPI = false, bool SP2 = true>
; __device__ __forceinline__ void gemm_phase(PG8_LAS unsigned char* lds, const Gemm g, const Sched& S, const Epi& E, int wave_s) {
;     ...
;             PG8_WAIT_V(8); PG8_WAIT_L(0); PG8_BAR; PG8_MMA(1, 0, At, B0); PG8_MMA(1, 1, At, B1); PG8_BAR; PG8_SCHED;
;             PG8_LDB(B0, 1, 0); PG8_LDB(B1, 1, 1); PG8_SCHED; PG8_LDA(At, 1, 0); PG8_STAGE(PG8_SA(0, 1), a2 + hstepA, voffA);
.Lrf_join:
	s_waitcnt vmcnt(8)
	s_waitcnt lgkmcnt(0)
	s_barrier
	v_mfma_f32_16x16x32_bf16 v[62:65], v[130:133], v[188:191], v[62:65]
	v_mfma_f32_16x16x32_bf16 v[58:61], v[158:161], v[188:191], v[58:61]
	v_mfma_f32_16x16x32_bf16 v[46:49], v[130:133], v[196:199], v[46:49]
	v_mfma_f32_16x16x32_bf16 v[42:45], v[158:161], v[196:199], v[42:45]
	v_mfma_f32_16x16x32_bf16 v[30:33], v[130:133], v[204:207], v[30:33]
	v_mfma_f32_16x16x32_bf16 v[26:29], v[158:161], v[204:207], v[26:29]
	v_mfma_f32_16x16x32_bf16 v[14:17], v[130:133], v[212:215], v[14:17]
	v_mfma_f32_16x16x32_bf16 v[10:13], v[158:161], v[212:215], v[10:13]
	v_mfma_f32_16x16x32_bf16 v[62:65], v[134:137], v[192:195], v[62:65]
	v_mfma_f32_16x16x32_bf16 v[58:61], v[162:165], v[192:195], v[58:61]
	v_mfma_f32_16x16x32_bf16 v[46:49], v[134:137], v[200:203], v[46:49]
	v_mfma_f32_16x16x32_bf16 v[42:45], v[162:165], v[200:203], v[42:45]
	v_mfma_f32_16x16x32_bf16 v[30:33], v[134:137], v[208:211], v[30:33]
	v_mfma_f32_16x16x32_bf16 v[26:29], v[162:165], v[208:211], v[26:29]
	v_mfma_f32_16x16x32_bf16 v[14:17], v[134:137], v[216:219], v[14:17]
	v_mfma_f32_16x16x32_bf16 v[10:13], v[162:165], v[216:219], v[10:13]
	v_mfma_f32_16x16x32_bf16 v[54:57], v[166:169], v[188:191], v[54:57]
	v_mfma_f32_16x16x32_bf16 v[50:53], v[180:183], v[188:191], v[50:53]
	v_mfma_f32_16x16x32_bf16 v[38:41], v[166:169], v[196:199], v[38:41]
	v_mfma_f32_16x16x32_bf16 v[34:37], v[180:183], v[196:199], v[34:37]
	v_mfma_f32_16x16x32_bf16 v[22:25], v[166:169], v[204:207], v[22:25]
	v_mfma_f32_16x16x32_bf16 v[18:21], v[180:183], v[204:207], v[18:21]
	v_mfma_f32_16x16x32_bf16 v[6:9], v[166:169], v[212:215], v[6:9]
	v_mfma_f32_16x16x32_bf16 v[2:5], v[180:183], v[212:215], v[2:5]
	v_mfma_f32_16x16x32_bf16 v[54:57], v[176:179], v[192:195], v[54:57]
	v_mfma_f32_16x16x32_bf16 v[50:53], v[184:187], v[192:195], v[50:53]
	v_mfma_f32_16x16x32_bf16 v[38:41], v[176:179], v[200:203], v[38:41]
	v_mfma_f32_16x16x32_bf16 v[34:37], v[184:187], v[200:203], v[34:37]
	v_mfma_f32_16x16x32_bf16 v[22:25], v[176:179], v[208:211], v[22:25]
	v_mfma_f32_16x16x32_bf16 v[18:21], v[184:187], v[208:211], v[18:21]
	v_mfma_f32_16x16x32_bf16 v[6:9], v[176:179], v[216:219], v[6:9]
	v_mfma_f32_16x16x32_bf16 v[2:5], v[184:187], v[216:219], v[2:5]
	s_barrier
	s_add_i32 s77, s74, 2
	s_lshr_b32 s32, s77, 4
	s_lshl_b32 s32, s32, 20
	s_bfe_u32 s100, s77, 0x20002
	s_lshl_b32 s100, s100, 17
	s_or_b32 s32, s32, s100
	s_and_b32 s100, s77, 2
	s_lshl_b32 s100, s100, 8
	s_or_b32 s32, s32, s100
	s_and_b32 s100, s92, 1
	s_lshr_b32 s32, s32, s100
	s_add_u32 s100, s94, s32
	s_addc_u32 s101, s95, 0
	s_cmp_eq_u32 s92, 0
	s_cbranch_scc0 .Lrf_ld_m1
	global_load_dwordx4 v[240:243], v250, s[100:101]
	global_load_dwordx4 v[244:247], v250, s[100:101] offset:16
	s_branch .Lrf_ld_done

; #define PG8_STAGE(bufoff, gbase, voff) do { _Pragma("unroll") for (int _i = 0; _i < 2; ++_i) \
;         __builtin_amdgcn_global_load_lds((const unsigned*)((const char*)(gbase) + (voff)[_i]), (PG8_LAS unsigned*)(lds + (bufoff) + ldsw + _i * 8192), 16, 0, 0); } while (0)
; #define PG8_LDA(dst, b, h) do { _Pragma("unroll") for (int m = 0; m < 4; ++m) _Pragma("unroll") for (int k = 0; k < 2; ++k) dst[m][k] = *(const PG8_LAS bf16x8*)(lds + PG8_SA(b, h) + aoff + m * 2048 + k * 1024); } while (0)
; #define PG8_LDB(dst, b, h) do { _Pragma("unroll") for (int n = 0; n < 2; ++n) _Pragma("unroll") for (int k = 0; k < 2; ++k) dst[n][k] = *(const PG8_LAS bf16x8*)(lds + PG8_SB(b, h) + boff + n * 2048 + k * 1024); } while (0)
; #define PG8_MMA(ai, bj, At, Bt) do { __builtin_amdgcn_s_setprio(1); _Pragma("unroll") for (int m = 0; m < 4; ++m) _Pragma("unroll") for (int n = 0; n < 2; ++n) _Pragma("unroll") for (int k = 0; k < 2; ++k) \
;         acc[ai][bj][m][n] = __builtin_amdgcn_mfma_f32_16x16x32_bf16(Bt[n][k], At[m][k], acc[ai][bj][m][n], 0, 0, 0); __builtin_amdgcn_s_setprio(0); } while (0)
; #define PG8_WAIT_V(n) asm volatile("s_waitcnt vmcnt(" #n ")" ::: "memory")
; #define PG8_WAIT_L(n) asm volatile("s_waitcnt lgkmcnt(" #n ")" ::: "memory")
; #define PG8_BAR __builtin_amdgcn_s_barrier()
; #define PG8_SCHED __builtin_amdgcn_sched_barrier(0)
; template <class Epi, class Sched, bool ALIGN_EPI = false, bool SP2 = true>
; __device__ __forceinline__ void gemm_phase(PG8_LAS unsigned char* lds, const Gemm g, const Sched& S, const Epi& E, int wave_s) {
;     ...
;             PG8_LDB(B0, 1, 0); PG8_LDB(B1, 1, 1); PG8_SCHED; PG8_LDA(At, 1, 0); PG8_STAGE(PG8_SA(0, 1), a2 + hstepA, voffA);
;             PG8_WAIT_V(8); PG8_WAIT_L(0); PG8_BAR; PG8_MMA(0, 0, At, B0); PG8_MMA(0, 1, At, B1); PG8_BAR; PG8_SCHED;
.Lrf_ld_done:
	s_add_i32 s75, 0, 0x18000
	s_add_i32 s76, 0, 0x1c000
	v_add_u32_e32 v162, s75, v170
	v_add_u32_e32 v175, s76, v170
	ds_read_b128 v[130:133], v162
	ds_read_b128 v[134:137], v162 offset:1024
	ds_read_b128 v[158:161], v162 offset:2048
	ds_read_b128 v[162:165], v162 offset:3072
	ds_read_b128 v[166:169], v175
	ds_read_b128 v[176:179], v175 offset:1024
	ds_read_b128 v[180:183], v175 offset:2048
	ds_read_b128 v[184:187], v175 offset:3072
	s_add_u32 s24, s28, 0x140000
	s_addc_u32 s25, s29, 0
	s_mov_b32 m0, s42
	v_lshl_add_u64 v[226:227], s[24:25], 0, v[144:145]
	ds_read_b128 v[188:191], v174 offset:32768
	ds_read_b128 v[192:195], v174 offset:33792
	ds_read_b128 v[196:199], v174 offset:34816
	ds_read_b128 v[200:203], v174 offset:35840
	ds_read_b128 v[204:207], v174 offset:36864
	ds_read_b128 v[208:211], v174 offset:37888
	ds_read_b128 v[212:215], v174 offset:38912
	ds_read_b128 v[216:219], v174 offset:39936
	global_load_lds_dwordx4 v[226:227], off
	v_lshl_add_u64 v[226:227], s[24:25], 0, v[140:141]
	s_mov_b32 m0, s43
	s_nop 0
	global_load_lds_dwordx4 v[226:227], off
	s_waitcnt vmcnt(10)
	s_waitcnt lgkmcnt(0)
	s_barrier
	v_mfma_f32_16x16x32_bf16 v[126:129], v[130:133], v[188:191], v[126:129]
	v_mfma_f32_16x16x32_bf16 v[122:125], v[158:161], v[188:191], v[122:125]
	v_mfma_f32_16x16x32_bf16 v[110:113], v[130:133], v[196:199], v[110:113]
	v_mfma_f32_16x16x32_bf16 v[106:109], v[158:161], v[196:199], v[106:109]
	v_mfma_f32_16x16x32_bf16 v[94:97], v[130:133], v[204:207], v[94:97]
	v_mfma_f32_16x16x32_bf16 v[90:93], v[158:161], v[204:207], v[90:93]
	v_mfma_f32_16x16x32_bf16 v[78:81], v[130:133], v[212:215], v[78:81]
	v_mfma_f32_16x16x32_bf16 v[74:77], v[158:161], v[212:215], v[74:77]
	v_mfma_f32_16x16x32_bf16 v[126:129], v[134:137], v[192:195], v[126:129]
	v_mfma_f32_16x16x32_bf16 v[122:125], v[162:165], v[192:195], v[122:125]
	v_mfma_f32_16x16x32_bf16 v[110:113], v[134:137], v[200:203], v[110:113]
	v_mfma_f32_16x16x32_bf16 v[106:109], v[162:165], v[200:203], v[106:109]
	v_mfma_f32_16x16x32_bf16 v[94:97], v[134:137], v[208:211], v[94:97]
	v_mfma_f32_16x16x32_bf16 v[90:93], v[162:165], v[208:211], v[90:93]
	v_mfma_f32_16x16x32_bf16 v[78:81], v[134:137], v[216:219], v[78:81]
	v_mfma_f32_16x16x32_bf16 v[74:77], v[162:165], v[216:219], v[74:77]
	v_mfma_f32_16x16x32_bf16 v[118:121], v[166:169], v[188:191], v[118:121]
	v_mfma_f32_16x16x32_bf16 v[114:117], v[180:183], v[188:191], v[114:117]
	v_mfma_f32_16x16x32_bf16 v[102:105], v[166:169], v[196:199], v[102:105]
	v_mfma_f32_16x16x32_bf16 v[98:101], v[180:183], v[196:199], v[98:101]
	v_mfma_f32_16x16x32_bf16 v[86:89], v[166:169], v[204:207], v[86:89]
	v_mfma_f32_16x16x32_bf16 v[82:85], v[180:183], v[204:207], v[82:85]
	v_mfma_f32_16x16x32_bf16 v[70:73], v[166:169], v[212:215], v[70:73]
	v_mfma_f32_16x16x32_bf16 v[66:69], v[180:183], v[212:215], v[66:69]
	v_mfma_f32_16x16x32_bf16 v[118:121], v[176:179], v[192:195], v[118:121]
	v_mfma_f32_16x16x32_bf16 v[114:117], v[184:187], v[192:195], v[114:117]
	v_mfma_f32_16x16x32_bf16 v[102:105], v[176:179], v[200:203], v[102:105]
	v_mfma_f32_16x16x32_bf16 v[98:101], v[184:187], v[200:203], v[98:101]
	v_mfma_f32_16x16x32_bf16 v[86:89], v[176:179], v[208:211], v[86:89]
	v_mfma_f32_16x16x32_bf16 v[82:85], v[184:187], v[208:211], v[82:85]
	v_mfma_f32_16x16x32_bf16 v[70:73], v[176:179], v[216:219], v[70:73]
	v_mfma_f32_16x16x32_bf16 v[66:69], v[184:187], v[216:219], v[66:69]
	s_barrier
; #define PG8_STAGE(bufoff, gbase, voff) do { _Pragma("unroll") for (int _i = 0; _i < 2; ++_i) \
;         __builtin_amdgcn_global_load_lds((const unsigned*)((const char*)(gbase) + (voff)[_i]), (PG8_LAS unsigned*)(lds + (bufoff) + ldsw + _i * 8192), 16, 0, 0); } while (0)
; #define PG8_LDA(dst, b, h) do { _Pragma("unroll") for (int m = 0; m < 4; ++m) _Pragma("unroll") for (int k = 0; k < 2; ++k) dst[m][k] = *(const PG8_LAS bf16x8*)(lds + PG8_SA(b, h) + aoff + m * 2048 + k * 1024); } while (0)
; #define PG8_MMA(ai, bj, At, Bt) do { __builtin_amdgcn_s_setprio(1); _Pragma("unroll") for (int m = 0; m < 4; ++m) _Pragma("unroll") for (int n = 0; n < 2; ++n) _Pragma("unroll") for (int k = 0; k < 2; ++k) \
;         acc[ai][bj][m][n] = __builtin_amdgcn_mfma_f32_16x16x32_bf16(Bt[n][k], At[m][k], acc[ai][bj][m][n], 0, 0, 0); __builtin_amdgcn_s_setprio(0); } while (0)
; #define PG8_WAIT_V(n) asm volatile("s_waitcnt vmcnt(" #n ")" ::: "memory")
; #define PG8_WAIT_L(n) asm volatile("s_waitcnt lgkmcnt(" #n ")" ::: "memory")
; #define PG8_BAR __builtin_amdgcn_s_barrier()
; #define PG8_SCHED __builtin_amdgcn_sched_barrier(0)
; template <class Epi, class Sched, bool ALIGN_EPI = false, bool SP2 = true>
; __device__ __forceinline__ void gemm_phase(PG8_LAS unsigned char* lds, const Gemm g, const Sched& S, const Epi& E, int wave_s) {
;     ...
;             PG8_LDA(At, 1, 1); PG8_STAGE(PG8_SB(1, 0), b3, voffB); PG8_STAGE(PG8_SB(1, 1), b3 + hstepB, voffB); PG8_STAGE(PG8_SA(1, 0), a3, voffA);
;             PG8_WAIT_V(8); PG8_WAIT_L(0); PG8_BAR; PG8_MMA(1, 0, At, B0); PG8_MMA(1, 1, At, B1); PG8_BAR; PG8_SCHED;
	s_add_i32 s77, s74, 2
	s_lshr_b32 s77, s77, 2
	s_and_b32 s32, s77, 3
	s_lshl_b32 s32, s32, 6
	s_lshr_b32 s77, s77, 2
	s_lshl_b32 s77, s77, 9
	s_or_b32 s77, s77, s32
	v_add_u32_e32 v253, s77, v252
	ds_read_b32 v251, v253
	s_add_i32 s24, s75, s34
	v_lshl_add_u64 v[146:147], v[146:147], 0, s[78:79]
	s_mov_b32 m0, s24
	ds_read_b128 v[188:191], v174 offset:49152
	ds_read_b128 v[192:195], v174 offset:50176
	ds_read_b128 v[196:199], v174 offset:51200
	ds_read_b128 v[200:203], v174 offset:52224
	ds_read_b128 v[204:207], v174 offset:53248
	ds_read_b128 v[208:211], v174 offset:54272
	ds_read_b128 v[212:215], v174 offset:55296
	ds_read_b128 v[216:219], v174 offset:56320
	global_load_lds_dwordx4 v[146:147], off
	s_add_i32 m0, s24, 0x2000
	s_add_u32 s24, s26, 0x80080
	v_lshl_add_u64 v[146:147], v[220:221], 0, s[78:79]
	s_addc_u32 s25, s27, 0
	s_add_i32 s26, s76, s34
	global_load_lds_dwordx4 v[146:147], off
	v_lshl_add_u64 v[146:147], s[24:25], 0, v[142:143]
	s_mov_b32 m0, s26
	s_nop 0
	global_load_lds_dwordx4 v[146:147], off
	v_lshl_add_u64 v[146:147], s[24:25], 0, v[138:139]
	s_add_i32 m0, s26, 0x2000
	s_nop 0
	global_load_lds_dwordx4 v[146:147], off
	v_lshl_add_u64 v[146:147], v[222:223], 0, s[78:79]
	s_mov_b32 m0, s40
	s_nop 0
	global_load_lds_dwordx4 v[146:147], off
	v_lshl_add_u64 v[146:147], v[224:225], 0, s[78:79]
	s_mov_b32 m0, s41
	s_nop 0
	global_load_lds_dwordx4 v[146:147], off
	s_waitcnt vmcnt(10)
	s_waitcnt lgkmcnt(0)
	v_rcp_f32_e32 v248, v251
	s_barrier
	v_mfma_f32_16x16x32_bf16 v[62:65], v[130:133], v[188:191], v[62:65]
	v_mfma_f32_16x16x32_bf16 v[58:61], v[158:161], v[188:191], v[58:61]
	v_mfma_f32_16x16x32_bf16 v[46:49], v[130:133], v[196:199], v[46:49]
	v_mfma_f32_16x16x32_bf16 v[42:45], v[158:161], v[196:199], v[42:45]
	v_mfma_f32_16x16x32_bf16 v[30:33], v[130:133], v[204:207], v[30:33]
	v_mfma_f32_16x16x32_bf16 v[26:29], v[158:161], v[204:207], v[26:29]
	v_mfma_f32_16x16x32_bf16 v[14:17], v[130:133], v[212:215], v[14:17]
	v_mfma_f32_16x16x32_bf16 v[10:13], v[158:161], v[212:215], v[10:13]
	v_mfma_f32_16x16x32_bf16 v[62:65], v[134:137], v[192:195], v[62:65]
	v_mfma_f32_16x16x32_bf16 v[58:61], v[162:165], v[192:195], v[58:61]
	v_mfma_f32_16x16x32_bf16 v[46:49], v[134:137], v[200:203], v[46:49]
	v_mfma_f32_16x16x32_bf16 v[42:45], v[162:165], v[200:203], v[42:45]
	v_mfma_f32_16x16x32_bf16 v[30:33], v[134:137], v[208:211], v[30:33]
	v_mfma_f32_16x16x32_bf16 v[26:29], v[162:165], v[208:211], v[26:29]
	v_mfma_f32_16x16x32_bf16 v[14:17], v[134:137], v[216:219], v[14:17]
	v_mfma_f32_16x16x32_bf16 v[10:13], v[162:165], v[216:219], v[10:13]
	v_mfma_f32_16x16x32_bf16 v[54:57], v[166:169], v[188:191], v[54:57]
	v_mfma_f32_16x16x32_bf16 v[50:53], v[180:183], v[188:191], v[50:53]
	v_mfma_f32_16x16x32_bf16 v[38:41], v[166:169], v[196:199], v[38:41]
	v_mfma_f32_16x16x32_bf16 v[34:37], v[180:183], v[196:199], v[34:37]
	v_mfma_f32_16x16x32_bf16 v[22:25], v[166:169], v[204:207], v[22:25]
	v_mfma_f32_16x16x32_bf16 v[18:21], v[180:183], v[204:207], v[18:21]
	v_mfma_f32_16x16x32_bf16 v[6:9], v[166:169], v[212:215], v[6:9]
	v_mfma_f32_16x16x32_bf16 v[2:5], v[180:183], v[212:215], v[2:5]
	v_mfma_f32_16x16x32_bf16 v[54:57], v[176:179], v[192:195], v[54:57]
	v_mfma_f32_16x16x32_bf16 v[50:53], v[184:187], v[192:195], v[50:53]
	v_mfma_f32_16x16x32_bf16 v[38:41], v[176:179], v[200:203], v[38:41]
	v_mfma_f32_16x16x32_bf16 v[34:37], v[184:187], v[200:203], v[34:37]
	v_mfma_f32_16x16x32_bf16 v[22:25], v[176:179], v[208:211], v[22:25]
	v_mfma_f32_16x16x32_bf16 v[18:21], v[184:187], v[208:211], v[18:21]
	v_mfma_f32_16x16x32_bf16 v[6:9], v[176:179], v[216:219], v[6:9]
	v_mfma_f32_16x16x32_bf16 v[2:5], v[184:187], v[216:219], v[2:5]
	s_barrier
	s_add_i32 s74, s74, 2
	s_add_u32 s72, s72, 0x100
	s_addc_u32 s73, s73, 0
	s_cmp_gt_u32 s74, 29
	s_mov_b64 s[24:25], s[6:7]
	s_cbranch_scc0 .LBB0_608
	s_and_b64 vcc, exec, s[16:17]
	s_cbranch_vccz .LBB0_611
	s_barrier
